# attention tile loop: 32 zero-init v_mov moved off the off-diagonal (hot) path onto the diagonal-tile path
# speedup vs baseline: 1.0086x; 1.0067x over previous
; __device__ __forceinline__ void attn_unit(const Params& P, int li, LAS unsigned char* lds, int b, int h, int qb, float lam, float one_m_li) {
;     ...
;             const bool diag = (t == cw);
;             if (diag) { p0 = f32x16{}; p1 = f32x16{}; }
.Lattn_diag_zero:
	v_mov_b32_e32 v64, 0
	v_mov_b32_e32 v65, 0
	v_mov_b32_e32 v66, 0
	v_mov_b32_e32 v67, 0
	v_mov_b32_e32 v68, 0
	v_mov_b32_e32 v69, 0
	v_mov_b32_e32 v70, 0
	v_mov_b32_e32 v71, 0
	v_mov_b32_e32 v72, 0
	v_mov_b32_e32 v73, 0
	v_mov_b32_e32 v74, 0
	v_mov_b32_e32 v75, 0
	v_mov_b32_e32 v76, 0
	v_mov_b32_e32 v77, 0
	v_mov_b32_e32 v78, 0
	v_mov_b32_e32 v79, 0
	v_mov_b32_e32 v80, 0
	v_mov_b32_e32 v81, 0
	v_mov_b32_e32 v82, 0
	v_mov_b32_e32 v83, 0
	v_mov_b32_e32 v84, 0
	v_mov_b32_e32 v85, 0
	v_mov_b32_e32 v86, 0
	v_mov_b32_e32 v87, 0
	v_mov_b32_e32 v88, 0
	v_mov_b32_e32 v89, 0
	v_mov_b32_e32 v90, 0
	v_mov_b32_e32 v91, 0
	v_mov_b32_e32 v92, 0
	v_mov_b32_e32 v93, 0
	v_mov_b32_e32 v94, 0
	v_mov_b32_e32 v95, 0
	s_branch .LBB0_417

; #define LAS __attribute__((address_space(3)))
; __device__ __forceinline__ float fadd_s(float a, float b) { float r; asm("v_add_f32_e32 %0, %1, %2" : "=v"(r) : "v"(a), "v"(b)); return r; }
; __device__ __forceinline__ float fma2_s(float a, float c) { float r; asm("v_fma_f32 %0, %1, 2.0, %2" : "=v"(r) : "v"(a), "v"(c)); return r; }
; __device__ __forceinline__ void attn_unit(const Params& P, int li, LAS unsigned char* lds, int b, int h, int qb, float lam, float one_m_li) {
;     ...
;         if (t <= cw) {
;             f32x16 p0, p1;
;             const LAS unsigned char* kp = cb + mp * 8192 + r32 * 128;
;             bf16x8 kf[8];
; #pragma unroll
;             for (int d0 = 0; d0 < 4; ++d0) { kf[2 * d0] = *(const LAS bf16x8*)(kp + coff[d0]); kf[2 * d0 + 1] = *(const LAS bf16x8*)(kp + 4096 + coff[d0]); }
;             const bool diag = (t == cw);
;             if (diag) { p0 = f32x16{}; p1 = f32x16{}; }
;             else {
;                 const float nc0 = -(sl * ((float)((cw - t) * 64) + qinf) + m), nc1 = fadd_s(nc0, sl32);
;                 float b0[4], b1[4];
;                 b0[0] = nc0; b0[1] = fadd_s(nc0, sl8); b0[2] = fma2_s(sl8, nc0); b0[3] = fadd_s(nc0, sl24);
;                 b1[0] = nc1; b1[1] = fadd_s(nc1, sl8); b1[2] = fma2_s(sl8, nc1); b1[3] = fadd_s(nc1, sl24);
; #pragma unroll
;                 for (int q = 0; q < 4; ++q) {
;                     p0[4 * q] = b0[q]; p0[4 * q + 1] = fadd_s(b0[q], sl); p0[4 * q + 2] = fma2_s(sl, b0[q]); p0[4 * q + 3] = fadd_s(b0[q], sl3);
;                     p1[4 * q] = b1[q]; p1[4 * q + 1] = fadd_s(b1[q], sl); p1[4 * q + 2] = fma2_s(sl, b1[q]); p1[4 * q + 3] = fadd_s(b1[q], sl3);
;                 }
;             }
.LBB0_414:
	s_cmp_lt_i32 s31, s4
	s_cbranch_scc1 .LBB0_427
	s_lshl_b32 s10, s21, 15
	s_and_b32 s22, s10, 0x18000
	v_add_u32_e32 v64, s22, v227
	v_add_u32_e32 v65, v64, v225
	ds_read_b128 v[124:127], v65
	ds_read_b128 v[116:119], v65 offset:4096
	v_add_u32_e32 v65, v64, v224
	ds_read_b128 v[120:123], v65
	ds_read_b128 v[108:111], v65 offset:4096
	v_add_u32_e32 v65, v64, v223
	v_add_u32_e32 v64, v64, v221
	ds_read_b128 v[112:115], v65
	ds_read_b128 v[100:103], v65 offset:4096
	ds_read_b128 v[104:107], v64
	ds_read_b128 v[96:99], v64 offset:4096
	s_cmp_eq_u32 s31, s4
	s_cselect_b64 s[22:23], -1, 0
	s_cmp_lg_u32 s31, s4
	s_cselect_b64 s[42:43], -1, 0
	s_and_b64 vcc, exec, s[22:23]
	s_cbranch_vccnz .Lattn_diag_zero
	s_sub_i32 s4, s31, s4
	s_lshl_b32 s4, s4, 6
	v_cvt_f32_i32_e32 v64, s4
	v_add_f32_e32 v64, v220, v64
	v_fma_f32 v64, v197, v64, v232
	v_xor_b32_e32 v80, 0x80000000, v64
	v_add_f32_e32 v64, v80, v201
	v_add_f32_e32 v84, v80, v199
	v_fma_f32 v88, v199, 2.0, v80
	v_add_f32_e32 v92, v80, v200
	v_add_f32_e32 v81, v80, v197
	v_fma_f32 v82, v197, 2.0, v80
	s_nop 0
	v_add_f32_e32 v68, v64, v199
	v_fma_f32 v72, v199, 2.0, v64
	v_add_f32_e32 v76, v64, v200
	v_add_f32_e32 v83, v80, v198
	v_add_f32_e32 v65, v64, v197
	v_fma_f32 v66, v197, 2.0, v64
	v_add_f32_e32 v67, v64, v198
	v_add_f32_e32 v85, v84, v197
	v_fma_f32 v86, v197, 2.0, v84
	v_add_f32_e32 v87, v84, v198
	s_nop 0
	v_add_f32_e32 v69, v68, v197
	v_fma_f32 v70, v197, 2.0, v68
	v_add_f32_e32 v71, v68, v198
	v_add_f32_e32 v89, v88, v197
	v_fma_f32 v90, v197, 2.0, v88
	v_add_f32_e32 v91, v88, v198
	v_add_f32_e32 v73, v72, v197
	v_fma_f32 v74, v197, 2.0, v72
	v_add_f32_e32 v75, v72, v198
	v_add_f32_e32 v93, v92, v197
	v_fma_f32 v94, v197, 2.0, v92
	v_add_f32_e32 v95, v92, v198
	v_add_f32_e32 v77, v76, v197
	v_fma_f32 v78, v197, 2.0, v76
	v_add_f32_e32 v79, v76, v198
